# cmp_unit top-16 ranking hand-unrolled (tie-break folded into ge/gt compares)
# baseline (speedup 1.0000x reference)
.LBB0_337:
	s_or_b64 exec, exec, s[4:5]
	v_or_b32_e32 v3, 26, v154
	v_cmp_le_u32_e32 vcc, v3, v0
	v_mov_b32_e32 v26, 0xf149f2ca
	v_mov_b32_e32 v28, 0xf149f2ca
	s_and_saveexec_b64 s[4:5], vcc
	v_cmp_eq_u32_e32 vcc, v3, v0
	v_cmp_eq_u32_e64 s[0:1], v3, v1
	s_or_b64 vcc, vcc, s[0:1]
	v_cndmask_b32_e32 v3, 0, v193, vcc
	v_add_f32_e32 v28, v3, v35
	s_or_b64 exec, exec, s[4:5]
	v_or_b32_e32 v3, 28, v154
	v_cmp_le_u32_e32 vcc, v3, v0
	s_and_saveexec_b64 s[4:5], vcc
	v_cmp_eq_u32_e32 vcc, v3, v0
	v_cmp_eq_u32_e64 s[0:1], v3, v1
	s_or_b64 vcc, vcc, s[0:1]
	v_cndmask_b32_e32 v3, 0, v193, vcc
	v_add_f32_e32 v26, v3, v32
	s_or_b64 exec, exec, s[4:5]
	v_or_b32_e32 v3, 30, v154
	v_cmp_le_u32_e32 vcc, v3, v0
	v_mov_b32_e32 v30, 0xf149f2ca
	s_and_saveexec_b64 s[4:5], vcc
	v_cmp_eq_u32_e32 vcc, v3, v0
	v_cmp_eq_u32_e64 s[0:1], v3, v1
	s_or_b64 vcc, vcc, s[0:1]
	v_cndmask_b32_e32 v3, 0, v193, vcc
	v_add_f32_e32 v30, v3, v33
	s_or_b64 exec, exec, s[4:5]
	v_cmp_eq_u32_e32 vcc, v154, v0
	v_cmp_eq_u32_e64 s[0:1], v154, v1
	s_or_b64 s[0:1], vcc, s[0:1]
	s_or_b64 vcc, s[38:39], s[0:1]
	v_cndmask_b32_e32 v1, 0, v193, vcc
	v_add_f32_e32 v1, v1, v36
	v_cmp_le_u32_e32 vcc, v154, v0
	ds_bpermute_b32 v36, v180, v4
	ds_bpermute_b32 v38, v180, v2
	v_cndmask_b32_e32 v32, v191, v1, vcc
	ds_bpermute_b32 v34, v180, v32
	ds_bpermute_b32 v40, v180, v8
	ds_bpermute_b32 v42, v180, v6
	ds_bpermute_b32 v44, v180, v12
	ds_bpermute_b32 v46, v180, v10
	s_waitcnt vmcnt(19)
	ds_bpermute_b32 v48, v180, v16
	ds_bpermute_b32 v50, v180, v14
	s_waitcnt vmcnt(18)
	ds_bpermute_b32 v52, v180, v20
	ds_bpermute_b32 v54, v180, v18
	s_waitcnt vmcnt(17)
	ds_bpermute_b32 v56, v180, v24
	ds_bpermute_b32 v58, v180, v22
	s_waitcnt vmcnt(16)
	ds_bpermute_b32 v60, v180, v28
	ds_bpermute_b32 v62, v180, v26
	s_waitcnt vmcnt(14)
	ds_bpermute_b32 v66, v180, v30
	s_xor_b64 s[0:1], s[38:39], -1
	v_cndmask_b32_e64 v68, 0, 1, s[0:1]
	v_mov_b32_e32 v1, v30
	s_waitcnt lgkmcnt(13)
	v_mov_b32_e32 v3, v34
	v_mov_b32_e32 v5, v36
	v_mov_b32_e32 v7, v38
	s_waitcnt lgkmcnt(12)
	v_mov_b32_e32 v9, v40
	s_waitcnt lgkmcnt(11)
	v_mov_b32_e32 v11, v42
	s_waitcnt lgkmcnt(10)
	v_mov_b32_e32 v13, v44
	s_waitcnt lgkmcnt(9)
	v_mov_b32_e32 v15, v46
	s_waitcnt lgkmcnt(8)
	v_mov_b32_e32 v17, v48
	s_waitcnt lgkmcnt(7)
	v_mov_b32_e32 v19, v50
	s_waitcnt lgkmcnt(6)
	v_mov_b32_e32 v21, v52
	s_waitcnt lgkmcnt(5)
	v_mov_b32_e32 v23, v54
	s_waitcnt lgkmcnt(4)
	v_mov_b32_e32 v25, v56
	s_waitcnt lgkmcnt(3)
	v_mov_b32_e32 v27, v58
	s_waitcnt lgkmcnt(2)
	v_mov_b32_e32 v29, v60
	s_waitcnt lgkmcnt(1)
	v_mov_b32_e32 v31, v62
	s_waitcnt lgkmcnt(0)
	v_mov_b32_e32 v33, v66
	v_mov_b32_e32 v35, v32
	v_mov_b32_e32 v37, v4
	v_mov_b32_e32 v39, v2
	v_mov_b32_e32 v41, v8
	v_mov_b32_e32 v43, v6
	v_mov_b32_e32 v45, v12
	v_mov_b32_e32 v47, v10
	v_mov_b32_e32 v49, v16
	v_mov_b32_e32 v51, v14
	v_mov_b32_e32 v53, v20
	v_mov_b32_e32 v55, v18
	v_mov_b32_e32 v57, v24
	v_mov_b32_e32 v59, v22
	v_mov_b32_e32 v61, v28
	v_mov_b32_e32 v63, v26
	v_mov_b32_e32 v67, v154
	v_mov_b32_e32 v69, v0
	s_waitcnt vmcnt(12)
	v_mov_b32_e32 v71, v68
	s_mov_b32 s36, 1
	v_mov_b32_e32 v70, 0
	s_mov_b32 s30, 16
	s_mov_b32 s31, 0
	v_mov_b32_e32 v72, 0
	ds_write2st64_b32 v155, v32, v4 offset1:1
	ds_write2st64_b32 v155, v2, v8 offset0:2 offset1:3
	ds_write2st64_b32 v155, v6, v12 offset0:4 offset1:5
	ds_write2st64_b32 v155, v10, v16 offset0:6 offset1:7
	ds_write2st64_b32 v155, v14, v20 offset0:8 offset1:9
	ds_write2st64_b32 v155, v18, v24 offset0:10 offset1:11
	ds_write2st64_b32 v155, v22, v28 offset0:12 offset1:13
	ds_write2st64_b32 v155, v26, v30 offset0:14 offset1:15
	s_waitcnt vmcnt(0) lgkmcnt(0)
	v_mov_b32_e32 v70, 0
	v_cmp_eq_u32_e64 s[10:11], 1, v154
	v_mov_b32_e32 v73, 0
	v_cmp_gt_f32_e64 s[12:13], v3, v35
	v_cmp_eq_f32_e64 s[14:15], v3, v35
	v_cmp_gt_f32_e64 s[0:1], v37, v35
	v_cmp_gt_f32_e64 s[2:3], v39, v35
	v_cmp_gt_f32_e64 s[4:5], v41, v35
	v_cmp_gt_f32_e64 s[6:7], v43, v35
	v_addc_co_u32_e64 v73, s[8:9], 0, v73, s[0:1]
	v_addc_co_u32_e64 v73, s[8:9], 0, v73, s[2:3]
	v_addc_co_u32_e64 v73, s[8:9], 0, v73, s[4:5]
	v_addc_co_u32_e64 v73, s[8:9], 0, v73, s[6:7]
	v_cmp_gt_f32_e64 s[0:1], v45, v35
	v_cmp_gt_f32_e64 s[2:3], v47, v35
	v_cmp_gt_f32_e64 s[4:5], v49, v35
	v_cmp_gt_f32_e64 s[6:7], v51, v35
	v_addc_co_u32_e64 v73, s[8:9], 0, v73, s[0:1]
	v_addc_co_u32_e64 v73, s[8:9], 0, v73, s[2:3]
	v_addc_co_u32_e64 v73, s[8:9], 0, v73, s[4:5]
	v_addc_co_u32_e64 v73, s[8:9], 0, v73, s[6:7]
	v_cmp_gt_f32_e64 s[0:1], v53, v35
	v_cmp_gt_f32_e64 s[2:3], v55, v35
	v_cmp_gt_f32_e64 s[4:5], v57, v35
	v_cmp_gt_f32_e64 s[6:7], v59, v35
	v_addc_co_u32_e64 v73, s[8:9], 0, v73, s[0:1]
	v_addc_co_u32_e64 v73, s[8:9], 0, v73, s[2:3]
	v_addc_co_u32_e64 v73, s[8:9], 0, v73, s[4:5]
	v_addc_co_u32_e64 v73, s[8:9], 0, v73, s[6:7]
	v_cmp_gt_f32_e64 s[0:1], v61, v35
	v_cmp_gt_f32_e64 s[2:3], v63, v35
	v_cmp_gt_f32_e64 s[4:5], v1, v35
	v_cmp_gt_f32_e64 s[6:7], v5, v35
	v_addc_co_u32_e64 v73, s[8:9], 0, v73, s[0:1]
	v_addc_co_u32_e64 v73, s[8:9], 0, v73, s[2:3]
	v_addc_co_u32_e64 v73, s[8:9], 0, v73, s[4:5]
	v_addc_co_u32_e64 v73, s[8:9], 0, v73, s[6:7]
	v_cmp_gt_f32_e64 s[0:1], v7, v35
	v_cmp_gt_f32_e64 s[2:3], v9, v35
	v_cmp_gt_f32_e64 s[4:5], v11, v35
	v_cmp_gt_f32_e64 s[6:7], v13, v35
	v_addc_co_u32_e64 v73, s[8:9], 0, v73, s[0:1]
	v_addc_co_u32_e64 v73, s[8:9], 0, v73, s[2:3]
	v_addc_co_u32_e64 v73, s[8:9], 0, v73, s[4:5]
	v_addc_co_u32_e64 v73, s[8:9], 0, v73, s[6:7]
	v_cmp_gt_f32_e64 s[0:1], v15, v35
	v_cmp_gt_f32_e64 s[2:3], v17, v35
	v_cmp_gt_f32_e64 s[4:5], v19, v35
	v_cmp_gt_f32_e64 s[6:7], v21, v35
	v_addc_co_u32_e64 v73, s[8:9], 0, v73, s[0:1]
	v_addc_co_u32_e64 v73, s[8:9], 0, v73, s[2:3]
	v_addc_co_u32_e64 v73, s[8:9], 0, v73, s[4:5]
	v_addc_co_u32_e64 v73, s[8:9], 0, v73, s[6:7]
	v_cmp_gt_f32_e64 s[0:1], v23, v35
	v_cmp_gt_f32_e64 s[2:3], v25, v35
	v_cmp_gt_f32_e64 s[4:5], v27, v35
	v_cmp_gt_f32_e64 s[6:7], v29, v35
	v_addc_co_u32_e64 v73, s[8:9], 0, v73, s[0:1]
	v_addc_co_u32_e64 v73, s[8:9], 0, v73, s[2:3]
	v_addc_co_u32_e64 v73, s[8:9], 0, v73, s[4:5]
	v_addc_co_u32_e64 v73, s[8:9], 0, v73, s[6:7]
	v_cmp_gt_f32_e64 s[0:1], v31, v35
	v_cmp_gt_f32_e64 s[2:3], v33, v35
	s_nop 1
	v_addc_co_u32_e64 v73, s[8:9], 0, v73, s[0:1]
	v_addc_co_u32_e64 v73, s[8:9], 0, v73, s[2:3]
	s_and_b64 s[14:15], s[14:15], s[10:11]
	s_or_b64 s[12:13], s[12:13], s[14:15]
	v_or_b32_e32 v74, 0, v154
	v_addc_co_u32_e64 v73, s[8:9], 0, v73, s[12:13]
	v_cmp_le_u32_e64 s[0:1], v74, v0
	v_lshlrev_b32_e64 v75, v74, 1
	v_cmp_gt_u32_e64 s[2:3], 16, v73
	s_and_b64 s[0:1], s[0:1], s[2:3]
	v_cndmask_b32_e64 v75, 0, v75, s[0:1]
	v_or_b32_e32 v70, v70, v75
	v_mov_b32_e32 v73, 0
	v_cmp_gt_f32_e64 s[12:13], v5, v37
	v_cmp_eq_f32_e64 s[14:15], v5, v37
	v_cmp_ge_f32_e64 s[0:1], v35, v37
	v_cmp_gt_f32_e64 s[2:3], v39, v37
	v_cmp_gt_f32_e64 s[4:5], v41, v37
	v_cmp_gt_f32_e64 s[6:7], v43, v37
	v_addc_co_u32_e64 v73, s[8:9], 0, v73, s[0:1]
	v_addc_co_u32_e64 v73, s[8:9], 0, v73, s[2:3]
	v_addc_co_u32_e64 v73, s[8:9], 0, v73, s[4:5]
	v_addc_co_u32_e64 v73, s[8:9], 0, v73, s[6:7]
	v_cmp_gt_f32_e64 s[0:1], v45, v37
	v_cmp_gt_f32_e64 s[2:3], v47, v37
	v_cmp_gt_f32_e64 s[4:5], v49, v37
	v_cmp_gt_f32_e64 s[6:7], v51, v37
	v_addc_co_u32_e64 v73, s[8:9], 0, v73, s[0:1]
	v_addc_co_u32_e64 v73, s[8:9], 0, v73, s[2:3]
	v_addc_co_u32_e64 v73, s[8:9], 0, v73, s[4:5]
	v_addc_co_u32_e64 v73, s[8:9], 0, v73, s[6:7]
	v_cmp_gt_f32_e64 s[0:1], v53, v37
	v_cmp_gt_f32_e64 s[2:3], v55, v37
	v_cmp_gt_f32_e64 s[4:5], v57, v37
	v_cmp_gt_f32_e64 s[6:7], v59, v37
	v_addc_co_u32_e64 v73, s[8:9], 0, v73, s[0:1]
	v_addc_co_u32_e64 v73, s[8:9], 0, v73, s[2:3]
	v_addc_co_u32_e64 v73, s[8:9], 0, v73, s[4:5]
	v_addc_co_u32_e64 v73, s[8:9], 0, v73, s[6:7]
	v_cmp_gt_f32_e64 s[0:1], v61, v37
	v_cmp_gt_f32_e64 s[2:3], v63, v37
	v_cmp_gt_f32_e64 s[4:5], v1, v37
	v_cmp_ge_f32_e64 s[6:7], v3, v37
	v_addc_co_u32_e64 v73, s[8:9], 0, v73, s[0:1]
	v_addc_co_u32_e64 v73, s[8:9], 0, v73, s[2:3]
	v_addc_co_u32_e64 v73, s[8:9], 0, v73, s[4:5]
	v_addc_co_u32_e64 v73, s[8:9], 0, v73, s[6:7]
	v_cmp_gt_f32_e64 s[0:1], v7, v37
	v_cmp_gt_f32_e64 s[2:3], v9, v37
	v_cmp_gt_f32_e64 s[4:5], v11, v37
	v_cmp_gt_f32_e64 s[6:7], v13, v37
	v_addc_co_u32_e64 v73, s[8:9], 0, v73, s[0:1]
	v_addc_co_u32_e64 v73, s[8:9], 0, v73, s[2:3]
	v_addc_co_u32_e64 v73, s[8:9], 0, v73, s[4:5]
	v_addc_co_u32_e64 v73, s[8:9], 0, v73, s[6:7]
	v_cmp_gt_f32_e64 s[0:1], v15, v37
	v_cmp_gt_f32_e64 s[2:3], v17, v37
	v_cmp_gt_f32_e64 s[4:5], v19, v37
	v_cmp_gt_f32_e64 s[6:7], v21, v37
	v_addc_co_u32_e64 v73, s[8:9], 0, v73, s[0:1]
	v_addc_co_u32_e64 v73, s[8:9], 0, v73, s[2:3]
	v_addc_co_u32_e64 v73, s[8:9], 0, v73, s[4:5]
	v_addc_co_u32_e64 v73, s[8:9], 0, v73, s[6:7]
	v_cmp_gt_f32_e64 s[0:1], v23, v37
	v_cmp_gt_f32_e64 s[2:3], v25, v37
	v_cmp_gt_f32_e64 s[4:5], v27, v37
	v_cmp_gt_f32_e64 s[6:7], v29, v37
	v_addc_co_u32_e64 v73, s[8:9], 0, v73, s[0:1]
	v_addc_co_u32_e64 v73, s[8:9], 0, v73, s[2:3]
	v_addc_co_u32_e64 v73, s[8:9], 0, v73, s[4:5]
	v_addc_co_u32_e64 v73, s[8:9], 0, v73, s[6:7]
	v_cmp_gt_f32_e64 s[0:1], v31, v37
	v_cmp_gt_f32_e64 s[2:3], v33, v37
	s_nop 1
	v_addc_co_u32_e64 v73, s[8:9], 0, v73, s[0:1]
	v_addc_co_u32_e64 v73, s[8:9], 0, v73, s[2:3]
	s_and_b64 s[14:15], s[14:15], s[10:11]
	s_or_b64 s[12:13], s[12:13], s[14:15]
	v_or_b32_e32 v74, 2, v154
	v_addc_co_u32_e64 v73, s[8:9], 0, v73, s[12:13]
	v_cmp_le_u32_e64 s[0:1], v74, v0
	v_lshlrev_b32_e64 v75, v74, 1
	v_cmp_gt_u32_e64 s[2:3], 16, v73
	s_and_b64 s[0:1], s[0:1], s[2:3]
	v_cndmask_b32_e64 v75, 0, v75, s[0:1]
	v_or_b32_e32 v70, v70, v75
	v_mov_b32_e32 v73, 0
	v_cmp_gt_f32_e64 s[12:13], v7, v39
	v_cmp_eq_f32_e64 s[14:15], v7, v39
	v_cmp_ge_f32_e64 s[0:1], v35, v39
	v_cmp_ge_f32_e64 s[2:3], v37, v39
	v_cmp_gt_f32_e64 s[4:5], v41, v39
	v_cmp_gt_f32_e64 s[6:7], v43, v39
	v_addc_co_u32_e64 v73, s[8:9], 0, v73, s[0:1]
	v_addc_co_u32_e64 v73, s[8:9], 0, v73, s[2:3]
	v_addc_co_u32_e64 v73, s[8:9], 0, v73, s[4:5]
	v_addc_co_u32_e64 v73, s[8:9], 0, v73, s[6:7]
	v_cmp_gt_f32_e64 s[0:1], v45, v39
	v_cmp_gt_f32_e64 s[2:3], v47, v39
	v_cmp_gt_f32_e64 s[4:5], v49, v39
	v_cmp_gt_f32_e64 s[6:7], v51, v39
	v_addc_co_u32_e64 v73, s[8:9], 0, v73, s[0:1]
	v_addc_co_u32_e64 v73, s[8:9], 0, v73, s[2:3]
	v_addc_co_u32_e64 v73, s[8:9], 0, v73, s[4:5]
	v_addc_co_u32_e64 v73, s[8:9], 0, v73, s[6:7]
	v_cmp_gt_f32_e64 s[0:1], v53, v39
	v_cmp_gt_f32_e64 s[2:3], v55, v39
	v_cmp_gt_f32_e64 s[4:5], v57, v39
	v_cmp_gt_f32_e64 s[6:7], v59, v39
	v_addc_co_u32_e64 v73, s[8:9], 0, v73, s[0:1]
	v_addc_co_u32_e64 v73, s[8:9], 0, v73, s[2:3]
	v_addc_co_u32_e64 v73, s[8:9], 0, v73, s[4:5]
	v_addc_co_u32_e64 v73, s[8:9], 0, v73, s[6:7]
	v_cmp_gt_f32_e64 s[0:1], v61, v39
	v_cmp_gt_f32_e64 s[2:3], v63, v39
	v_cmp_gt_f32_e64 s[4:5], v1, v39
	v_cmp_ge_f32_e64 s[6:7], v3, v39
	v_addc_co_u32_e64 v73, s[8:9], 0, v73, s[0:1]
	v_addc_co_u32_e64 v73, s[8:9], 0, v73, s[2:3]
	v_addc_co_u32_e64 v73, s[8:9], 0, v73, s[4:5]
	v_addc_co_u32_e64 v73, s[8:9], 0, v73, s[6:7]
	v_cmp_ge_f32_e64 s[0:1], v5, v39
	v_cmp_gt_f32_e64 s[2:3], v9, v39
	v_cmp_gt_f32_e64 s[4:5], v11, v39
	v_cmp_gt_f32_e64 s[6:7], v13, v39
	v_addc_co_u32_e64 v73, s[8:9], 0, v73, s[0:1]
	v_addc_co_u32_e64 v73, s[8:9], 0, v73, s[2:3]
	v_addc_co_u32_e64 v73, s[8:9], 0, v73, s[4:5]
	v_addc_co_u32_e64 v73, s[8:9], 0, v73, s[6:7]
	v_cmp_gt_f32_e64 s[0:1], v15, v39
	v_cmp_gt_f32_e64 s[2:3], v17, v39
	v_cmp_gt_f32_e64 s[4:5], v19, v39
	v_cmp_gt_f32_e64 s[6:7], v21, v39
	v_addc_co_u32_e64 v73, s[8:9], 0, v73, s[0:1]
	v_addc_co_u32_e64 v73, s[8:9], 0, v73, s[2:3]
	v_addc_co_u32_e64 v73, s[8:9], 0, v73, s[4:5]
	v_addc_co_u32_e64 v73, s[8:9], 0, v73, s[6:7]
	v_cmp_gt_f32_e64 s[0:1], v23, v39
	v_cmp_gt_f32_e64 s[2:3], v25, v39
	v_cmp_gt_f32_e64 s[4:5], v27, v39
	v_cmp_gt_f32_e64 s[6:7], v29, v39
	v_addc_co_u32_e64 v73, s[8:9], 0, v73, s[0:1]
	v_addc_co_u32_e64 v73, s[8:9], 0, v73, s[2:3]
	v_addc_co_u32_e64 v73, s[8:9], 0, v73, s[4:5]
	v_addc_co_u32_e64 v73, s[8:9], 0, v73, s[6:7]
	v_cmp_gt_f32_e64 s[0:1], v31, v39
	v_cmp_gt_f32_e64 s[2:3], v33, v39
	s_nop 1
	v_addc_co_u32_e64 v73, s[8:9], 0, v73, s[0:1]
	v_addc_co_u32_e64 v73, s[8:9], 0, v73, s[2:3]
	s_and_b64 s[14:15], s[14:15], s[10:11]
	s_or_b64 s[12:13], s[12:13], s[14:15]
	v_or_b32_e32 v74, 4, v154
	v_addc_co_u32_e64 v73, s[8:9], 0, v73, s[12:13]
	v_cmp_le_u32_e64 s[0:1], v74, v0
	v_lshlrev_b32_e64 v75, v74, 1
	v_cmp_gt_u32_e64 s[2:3], 16, v73
	s_and_b64 s[0:1], s[0:1], s[2:3]
	v_cndmask_b32_e64 v75, 0, v75, s[0:1]
	v_or_b32_e32 v70, v70, v75
	v_mov_b32_e32 v73, 0
	v_cmp_gt_f32_e64 s[12:13], v9, v41
	v_cmp_eq_f32_e64 s[14:15], v9, v41
	v_cmp_ge_f32_e64 s[0:1], v35, v41
	v_cmp_ge_f32_e64 s[2:3], v37, v41
	v_cmp_ge_f32_e64 s[4:5], v39, v41
	v_cmp_gt_f32_e64 s[6:7], v43, v41
	v_addc_co_u32_e64 v73, s[8:9], 0, v73, s[0:1]
	v_addc_co_u32_e64 v73, s[8:9], 0, v73, s[2:3]
	v_addc_co_u32_e64 v73, s[8:9], 0, v73, s[4:5]
	v_addc_co_u32_e64 v73, s[8:9], 0, v73, s[6:7]
	v_cmp_gt_f32_e64 s[0:1], v45, v41
	v_cmp_gt_f32_e64 s[2:3], v47, v41
	v_cmp_gt_f32_e64 s[4:5], v49, v41
	v_cmp_gt_f32_e64 s[6:7], v51, v41
	v_addc_co_u32_e64 v73, s[8:9], 0, v73, s[0:1]
	v_addc_co_u32_e64 v73, s[8:9], 0, v73, s[2:3]
	v_addc_co_u32_e64 v73, s[8:9], 0, v73, s[4:5]
	v_addc_co_u32_e64 v73, s[8:9], 0, v73, s[6:7]
	v_cmp_gt_f32_e64 s[0:1], v53, v41
	v_cmp_gt_f32_e64 s[2:3], v55, v41
	v_cmp_gt_f32_e64 s[4:5], v57, v41
	v_cmp_gt_f32_e64 s[6:7], v59, v41
	v_addc_co_u32_e64 v73, s[8:9], 0, v73, s[0:1]
	v_addc_co_u32_e64 v73, s[8:9], 0, v73, s[2:3]
	v_addc_co_u32_e64 v73, s[8:9], 0, v73, s[4:5]
	v_addc_co_u32_e64 v73, s[8:9], 0, v73, s[6:7]
	v_cmp_gt_f32_e64 s[0:1], v61, v41
	v_cmp_gt_f32_e64 s[2:3], v63, v41
	v_cmp_gt_f32_e64 s[4:5], v1, v41
	v_cmp_ge_f32_e64 s[6:7], v3, v41
	v_addc_co_u32_e64 v73, s[8:9], 0, v73, s[0:1]
	v_addc_co_u32_e64 v73, s[8:9], 0, v73, s[2:3]
	v_addc_co_u32_e64 v73, s[8:9], 0, v73, s[4:5]
	v_addc_co_u32_e64 v73, s[8:9], 0, v73, s[6:7]
	v_cmp_ge_f32_e64 s[0:1], v5, v41
	v_cmp_ge_f32_e64 s[2:3], v7, v41
	v_cmp_gt_f32_e64 s[4:5], v11, v41
	v_cmp_gt_f32_e64 s[6:7], v13, v41
	v_addc_co_u32_e64 v73, s[8:9], 0, v73, s[0:1]
	v_addc_co_u32_e64 v73, s[8:9], 0, v73, s[2:3]
	v_addc_co_u32_e64 v73, s[8:9], 0, v73, s[4:5]
	v_addc_co_u32_e64 v73, s[8:9], 0, v73, s[6:7]
	v_cmp_gt_f32_e64 s[0:1], v15, v41
	v_cmp_gt_f32_e64 s[2:3], v17, v41
	v_cmp_gt_f32_e64 s[4:5], v19, v41
	v_cmp_gt_f32_e64 s[6:7], v21, v41
	v_addc_co_u32_e64 v73, s[8:9], 0, v73, s[0:1]
	v_addc_co_u32_e64 v73, s[8:9], 0, v73, s[2:3]
	v_addc_co_u32_e64 v73, s[8:9], 0, v73, s[4:5]
	v_addc_co_u32_e64 v73, s[8:9], 0, v73, s[6:7]
	v_cmp_gt_f32_e64 s[0:1], v23, v41
	v_cmp_gt_f32_e64 s[2:3], v25, v41
	v_cmp_gt_f32_e64 s[4:5], v27, v41
	v_cmp_gt_f32_e64 s[6:7], v29, v41
	v_addc_co_u32_e64 v73, s[8:9], 0, v73, s[0:1]
	v_addc_co_u32_e64 v73, s[8:9], 0, v73, s[2:3]
	v_addc_co_u32_e64 v73, s[8:9], 0, v73, s[4:5]
	v_addc_co_u32_e64 v73, s[8:9], 0, v73, s[6:7]
	v_cmp_gt_f32_e64 s[0:1], v31, v41
	v_cmp_gt_f32_e64 s[2:3], v33, v41
	s_nop 1
	v_addc_co_u32_e64 v73, s[8:9], 0, v73, s[0:1]
	v_addc_co_u32_e64 v73, s[8:9], 0, v73, s[2:3]
	s_and_b64 s[14:15], s[14:15], s[10:11]
	s_or_b64 s[12:13], s[12:13], s[14:15]
	v_or_b32_e32 v74, 6, v154
	v_addc_co_u32_e64 v73, s[8:9], 0, v73, s[12:13]
	v_cmp_le_u32_e64 s[0:1], v74, v0
	v_lshlrev_b32_e64 v75, v74, 1
	v_cmp_gt_u32_e64 s[2:3], 16, v73
	s_and_b64 s[0:1], s[0:1], s[2:3]
	v_cndmask_b32_e64 v75, 0, v75, s[0:1]
	v_or_b32_e32 v70, v70, v75
	v_mov_b32_e32 v73, 0
	v_cmp_gt_f32_e64 s[12:13], v11, v43
	v_cmp_eq_f32_e64 s[14:15], v11, v43
	v_cmp_ge_f32_e64 s[0:1], v35, v43
	v_cmp_ge_f32_e64 s[2:3], v37, v43
	v_cmp_ge_f32_e64 s[4:5], v39, v43
	v_cmp_ge_f32_e64 s[6:7], v41, v43
	v_addc_co_u32_e64 v73, s[8:9], 0, v73, s[0:1]
	v_addc_co_u32_e64 v73, s[8:9], 0, v73, s[2:3]
	v_addc_co_u32_e64 v73, s[8:9], 0, v73, s[4:5]
	v_addc_co_u32_e64 v73, s[8:9], 0, v73, s[6:7]
	v_cmp_gt_f32_e64 s[0:1], v45, v43
	v_cmp_gt_f32_e64 s[2:3], v47, v43
	v_cmp_gt_f32_e64 s[4:5], v49, v43
	v_cmp_gt_f32_e64 s[6:7], v51, v43
	v_addc_co_u32_e64 v73, s[8:9], 0, v73, s[0:1]
	v_addc_co_u32_e64 v73, s[8:9], 0, v73, s[2:3]
	v_addc_co_u32_e64 v73, s[8:9], 0, v73, s[4:5]
	v_addc_co_u32_e64 v73, s[8:9], 0, v73, s[6:7]
	v_cmp_gt_f32_e64 s[0:1], v53, v43
	v_cmp_gt_f32_e64 s[2:3], v55, v43
	v_cmp_gt_f32_e64 s[4:5], v57, v43
	v_cmp_gt_f32_e64 s[6:7], v59, v43
	v_addc_co_u32_e64 v73, s[8:9], 0, v73, s[0:1]
	v_addc_co_u32_e64 v73, s[8:9], 0, v73, s[2:3]
	v_addc_co_u32_e64 v73, s[8:9], 0, v73, s[4:5]
	v_addc_co_u32_e64 v73, s[8:9], 0, v73, s[6:7]
	v_cmp_gt_f32_e64 s[0:1], v61, v43
	v_cmp_gt_f32_e64 s[2:3], v63, v43
	v_cmp_gt_f32_e64 s[4:5], v1, v43
	v_cmp_ge_f32_e64 s[6:7], v3, v43
	v_addc_co_u32_e64 v73, s[8:9], 0, v73, s[0:1]
	v_addc_co_u32_e64 v73, s[8:9], 0, v73, s[2:3]
	v_addc_co_u32_e64 v73, s[8:9], 0, v73, s[4:5]
	v_addc_co_u32_e64 v73, s[8:9], 0, v73, s[6:7]
	v_cmp_ge_f32_e64 s[0:1], v5, v43
	v_cmp_ge_f32_e64 s[2:3], v7, v43
	v_cmp_ge_f32_e64 s[4:5], v9, v43
	v_cmp_gt_f32_e64 s[6:7], v13, v43
	v_addc_co_u32_e64 v73, s[8:9], 0, v73, s[0:1]
	v_addc_co_u32_e64 v73, s[8:9], 0, v73, s[2:3]
	v_addc_co_u32_e64 v73, s[8:9], 0, v73, s[4:5]
	v_addc_co_u32_e64 v73, s[8:9], 0, v73, s[6:7]
	v_cmp_gt_f32_e64 s[0:1], v15, v43
	v_cmp_gt_f32_e64 s[2:3], v17, v43
	v_cmp_gt_f32_e64 s[4:5], v19, v43
	v_cmp_gt_f32_e64 s[6:7], v21, v43
	v_addc_co_u32_e64 v73, s[8:9], 0, v73, s[0:1]
	v_addc_co_u32_e64 v73, s[8:9], 0, v73, s[2:3]
	v_addc_co_u32_e64 v73, s[8:9], 0, v73, s[4:5]
	v_addc_co_u32_e64 v73, s[8:9], 0, v73, s[6:7]
	v_cmp_gt_f32_e64 s[0:1], v23, v43
	v_cmp_gt_f32_e64 s[2:3], v25, v43
	v_cmp_gt_f32_e64 s[4:5], v27, v43
	v_cmp_gt_f32_e64 s[6:7], v29, v43
	v_addc_co_u32_e64 v73, s[8:9], 0, v73, s[0:1]
	v_addc_co_u32_e64 v73, s[8:9], 0, v73, s[2:3]
	v_addc_co_u32_e64 v73, s[8:9], 0, v73, s[4:5]
	v_addc_co_u32_e64 v73, s[8:9], 0, v73, s[6:7]
	v_cmp_gt_f32_e64 s[0:1], v31, v43
	v_cmp_gt_f32_e64 s[2:3], v33, v43
	s_nop 1
	v_addc_co_u32_e64 v73, s[8:9], 0, v73, s[0:1]
	v_addc_co_u32_e64 v73, s[8:9], 0, v73, s[2:3]
	s_and_b64 s[14:15], s[14:15], s[10:11]
	s_or_b64 s[12:13], s[12:13], s[14:15]
	v_or_b32_e32 v74, 8, v154
	v_addc_co_u32_e64 v73, s[8:9], 0, v73, s[12:13]
	v_cmp_le_u32_e64 s[0:1], v74, v0
	v_lshlrev_b32_e64 v75, v74, 1
	v_cmp_gt_u32_e64 s[2:3], 16, v73
	s_and_b64 s[0:1], s[0:1], s[2:3]
	v_cndmask_b32_e64 v75, 0, v75, s[0:1]
	v_or_b32_e32 v70, v70, v75
	v_mov_b32_e32 v73, 0
	v_cmp_gt_f32_e64 s[12:13], v13, v45
	v_cmp_eq_f32_e64 s[14:15], v13, v45
	v_cmp_ge_f32_e64 s[0:1], v35, v45
	v_cmp_ge_f32_e64 s[2:3], v37, v45
	v_cmp_ge_f32_e64 s[4:5], v39, v45
	v_cmp_ge_f32_e64 s[6:7], v41, v45
	v_addc_co_u32_e64 v73, s[8:9], 0, v73, s[0:1]
	v_addc_co_u32_e64 v73, s[8:9], 0, v73, s[2:3]
	v_addc_co_u32_e64 v73, s[8:9], 0, v73, s[4:5]
	v_addc_co_u32_e64 v73, s[8:9], 0, v73, s[6:7]
	v_cmp_ge_f32_e64 s[0:1], v43, v45
	v_cmp_gt_f32_e64 s[2:3], v47, v45
	v_cmp_gt_f32_e64 s[4:5], v49, v45
	v_cmp_gt_f32_e64 s[6:7], v51, v45
	v_addc_co_u32_e64 v73, s[8:9], 0, v73, s[0:1]
	v_addc_co_u32_e64 v73, s[8:9], 0, v73, s[2:3]
	v_addc_co_u32_e64 v73, s[8:9], 0, v73, s[4:5]
	v_addc_co_u32_e64 v73, s[8:9], 0, v73, s[6:7]
	v_cmp_gt_f32_e64 s[0:1], v53, v45
	v_cmp_gt_f32_e64 s[2:3], v55, v45
	v_cmp_gt_f32_e64 s[4:5], v57, v45
	v_cmp_gt_f32_e64 s[6:7], v59, v45
	v_addc_co_u32_e64 v73, s[8:9], 0, v73, s[0:1]
	v_addc_co_u32_e64 v73, s[8:9], 0, v73, s[2:3]
	v_addc_co_u32_e64 v73, s[8:9], 0, v73, s[4:5]
	v_addc_co_u32_e64 v73, s[8:9], 0, v73, s[6:7]
	v_cmp_gt_f32_e64 s[0:1], v61, v45
	v_cmp_gt_f32_e64 s[2:3], v63, v45
	v_cmp_gt_f32_e64 s[4:5], v1, v45
	v_cmp_ge_f32_e64 s[6:7], v3, v45
	v_addc_co_u32_e64 v73, s[8:9], 0, v73, s[0:1]
	v_addc_co_u32_e64 v73, s[8:9], 0, v73, s[2:3]
	v_addc_co_u32_e64 v73, s[8:9], 0, v73, s[4:5]
	v_addc_co_u32_e64 v73, s[8:9], 0, v73, s[6:7]
	v_cmp_ge_f32_e64 s[0:1], v5, v45
	v_cmp_ge_f32_e64 s[2:3], v7, v45
	v_cmp_ge_f32_e64 s[4:5], v9, v45
	v_cmp_ge_f32_e64 s[6:7], v11, v45
	v_addc_co_u32_e64 v73, s[8:9], 0, v73, s[0:1]
	v_addc_co_u32_e64 v73, s[8:9], 0, v73, s[2:3]
	v_addc_co_u32_e64 v73, s[8:9], 0, v73, s[4:5]
	v_addc_co_u32_e64 v73, s[8:9], 0, v73, s[6:7]
	v_cmp_gt_f32_e64 s[0:1], v15, v45
	v_cmp_gt_f32_e64 s[2:3], v17, v45
	v_cmp_gt_f32_e64 s[4:5], v19, v45
	v_cmp_gt_f32_e64 s[6:7], v21, v45
	v_addc_co_u32_e64 v73, s[8:9], 0, v73, s[0:1]
	v_addc_co_u32_e64 v73, s[8:9], 0, v73, s[2:3]
	v_addc_co_u32_e64 v73, s[8:9], 0, v73, s[4:5]
	v_addc_co_u32_e64 v73, s[8:9], 0, v73, s[6:7]
	v_cmp_gt_f32_e64 s[0:1], v23, v45
	v_cmp_gt_f32_e64 s[2:3], v25, v45
	v_cmp_gt_f32_e64 s[4:5], v27, v45
	v_cmp_gt_f32_e64 s[6:7], v29, v45
	v_addc_co_u32_e64 v73, s[8:9], 0, v73, s[0:1]
	v_addc_co_u32_e64 v73, s[8:9], 0, v73, s[2:3]
	v_addc_co_u32_e64 v73, s[8:9], 0, v73, s[4:5]
	v_addc_co_u32_e64 v73, s[8:9], 0, v73, s[6:7]
	v_cmp_gt_f32_e64 s[0:1], v31, v45
	v_cmp_gt_f32_e64 s[2:3], v33, v45
	s_nop 1
	v_addc_co_u32_e64 v73, s[8:9], 0, v73, s[0:1]
	v_addc_co_u32_e64 v73, s[8:9], 0, v73, s[2:3]
	s_and_b64 s[14:15], s[14:15], s[10:11]
	s_or_b64 s[12:13], s[12:13], s[14:15]
	v_or_b32_e32 v74, 10, v154
	v_addc_co_u32_e64 v73, s[8:9], 0, v73, s[12:13]
	v_cmp_le_u32_e64 s[0:1], v74, v0
	v_lshlrev_b32_e64 v75, v74, 1
	v_cmp_gt_u32_e64 s[2:3], 16, v73
	s_and_b64 s[0:1], s[0:1], s[2:3]
	v_cndmask_b32_e64 v75, 0, v75, s[0:1]
	v_or_b32_e32 v70, v70, v75
	v_mov_b32_e32 v73, 0
	v_cmp_gt_f32_e64 s[12:13], v15, v47
	v_cmp_eq_f32_e64 s[14:15], v15, v47
	v_cmp_ge_f32_e64 s[0:1], v35, v47
	v_cmp_ge_f32_e64 s[2:3], v37, v47
	v_cmp_ge_f32_e64 s[4:5], v39, v47
	v_cmp_ge_f32_e64 s[6:7], v41, v47
	v_addc_co_u32_e64 v73, s[8:9], 0, v73, s[0:1]
	v_addc_co_u32_e64 v73, s[8:9], 0, v73, s[2:3]
	v_addc_co_u32_e64 v73, s[8:9], 0, v73, s[4:5]
	v_addc_co_u32_e64 v73, s[8:9], 0, v73, s[6:7]
	v_cmp_ge_f32_e64 s[0:1], v43, v47
	v_cmp_ge_f32_e64 s[2:3], v45, v47
	v_cmp_gt_f32_e64 s[4:5], v49, v47
	v_cmp_gt_f32_e64 s[6:7], v51, v47
	v_addc_co_u32_e64 v73, s[8:9], 0, v73, s[0:1]
	v_addc_co_u32_e64 v73, s[8:9], 0, v73, s[2:3]
	v_addc_co_u32_e64 v73, s[8:9], 0, v73, s[4:5]
	v_addc_co_u32_e64 v73, s[8:9], 0, v73, s[6:7]
	v_cmp_gt_f32_e64 s[0:1], v53, v47
	v_cmp_gt_f32_e64 s[2:3], v55, v47
	v_cmp_gt_f32_e64 s[4:5], v57, v47
	v_cmp_gt_f32_e64 s[6:7], v59, v47
	v_addc_co_u32_e64 v73, s[8:9], 0, v73, s[0:1]
	v_addc_co_u32_e64 v73, s[8:9], 0, v73, s[2:3]
	v_addc_co_u32_e64 v73, s[8:9], 0, v73, s[4:5]
	v_addc_co_u32_e64 v73, s[8:9], 0, v73, s[6:7]
	v_cmp_gt_f32_e64 s[0:1], v61, v47
	v_cmp_gt_f32_e64 s[2:3], v63, v47
	v_cmp_gt_f32_e64 s[4:5], v1, v47
	v_cmp_ge_f32_e64 s[6:7], v3, v47
	v_addc_co_u32_e64 v73, s[8:9], 0, v73, s[0:1]
	v_addc_co_u32_e64 v73, s[8:9], 0, v73, s[2:3]
	v_addc_co_u32_e64 v73, s[8:9], 0, v73, s[4:5]
	v_addc_co_u32_e64 v73, s[8:9], 0, v73, s[6:7]
	v_cmp_ge_f32_e64 s[0:1], v5, v47
	v_cmp_ge_f32_e64 s[2:3], v7, v47
	v_cmp_ge_f32_e64 s[4:5], v9, v47
	v_cmp_ge_f32_e64 s[6:7], v11, v47
	v_addc_co_u32_e64 v73, s[8:9], 0, v73, s[0:1]
	v_addc_co_u32_e64 v73, s[8:9], 0, v73, s[2:3]
	v_addc_co_u32_e64 v73, s[8:9], 0, v73, s[4:5]
	v_addc_co_u32_e64 v73, s[8:9], 0, v73, s[6:7]
	v_cmp_ge_f32_e64 s[0:1], v13, v47
	v_cmp_gt_f32_e64 s[2:3], v17, v47
	v_cmp_gt_f32_e64 s[4:5], v19, v47
	v_cmp_gt_f32_e64 s[6:7], v21, v47
	v_addc_co_u32_e64 v73, s[8:9], 0, v73, s[0:1]
	v_addc_co_u32_e64 v73, s[8:9], 0, v73, s[2:3]
	v_addc_co_u32_e64 v73, s[8:9], 0, v73, s[4:5]
	v_addc_co_u32_e64 v73, s[8:9], 0, v73, s[6:7]
	v_cmp_gt_f32_e64 s[0:1], v23, v47
	v_cmp_gt_f32_e64 s[2:3], v25, v47
	v_cmp_gt_f32_e64 s[4:5], v27, v47
	v_cmp_gt_f32_e64 s[6:7], v29, v47
	v_addc_co_u32_e64 v73, s[8:9], 0, v73, s[0:1]
	v_addc_co_u32_e64 v73, s[8:9], 0, v73, s[2:3]
	v_addc_co_u32_e64 v73, s[8:9], 0, v73, s[4:5]
	v_addc_co_u32_e64 v73, s[8:9], 0, v73, s[6:7]
	v_cmp_gt_f32_e64 s[0:1], v31, v47
	v_cmp_gt_f32_e64 s[2:3], v33, v47
	s_nop 1
	v_addc_co_u32_e64 v73, s[8:9], 0, v73, s[0:1]
	v_addc_co_u32_e64 v73, s[8:9], 0, v73, s[2:3]
	s_and_b64 s[14:15], s[14:15], s[10:11]
	s_or_b64 s[12:13], s[12:13], s[14:15]
	v_or_b32_e32 v74, 12, v154
	v_addc_co_u32_e64 v73, s[8:9], 0, v73, s[12:13]
	v_cmp_le_u32_e64 s[0:1], v74, v0
	v_lshlrev_b32_e64 v75, v74, 1
	v_cmp_gt_u32_e64 s[2:3], 16, v73
	s_and_b64 s[0:1], s[0:1], s[2:3]
	v_cndmask_b32_e64 v75, 0, v75, s[0:1]
	v_or_b32_e32 v70, v70, v75
	v_mov_b32_e32 v73, 0
	v_cmp_gt_f32_e64 s[12:13], v17, v49
	v_cmp_eq_f32_e64 s[14:15], v17, v49
	v_cmp_ge_f32_e64 s[0:1], v35, v49
	v_cmp_ge_f32_e64 s[2:3], v37, v49
	v_cmp_ge_f32_e64 s[4:5], v39, v49
	v_cmp_ge_f32_e64 s[6:7], v41, v49
	v_addc_co_u32_e64 v73, s[8:9], 0, v73, s[0:1]
	v_addc_co_u32_e64 v73, s[8:9], 0, v73, s[2:3]
	v_addc_co_u32_e64 v73, s[8:9], 0, v73, s[4:5]
	v_addc_co_u32_e64 v73, s[8:9], 0, v73, s[6:7]
	v_cmp_ge_f32_e64 s[0:1], v43, v49
	v_cmp_ge_f32_e64 s[2:3], v45, v49
	v_cmp_ge_f32_e64 s[4:5], v47, v49
	v_cmp_gt_f32_e64 s[6:7], v51, v49
	v_addc_co_u32_e64 v73, s[8:9], 0, v73, s[0:1]
	v_addc_co_u32_e64 v73, s[8:9], 0, v73, s[2:3]
	v_addc_co_u32_e64 v73, s[8:9], 0, v73, s[4:5]
	v_addc_co_u32_e64 v73, s[8:9], 0, v73, s[6:7]
	v_cmp_gt_f32_e64 s[0:1], v53, v49
	v_cmp_gt_f32_e64 s[2:3], v55, v49
	v_cmp_gt_f32_e64 s[4:5], v57, v49
	v_cmp_gt_f32_e64 s[6:7], v59, v49
	v_addc_co_u32_e64 v73, s[8:9], 0, v73, s[0:1]
	v_addc_co_u32_e64 v73, s[8:9], 0, v73, s[2:3]
	v_addc_co_u32_e64 v73, s[8:9], 0, v73, s[4:5]
	v_addc_co_u32_e64 v73, s[8:9], 0, v73, s[6:7]
	v_cmp_gt_f32_e64 s[0:1], v61, v49
	v_cmp_gt_f32_e64 s[2:3], v63, v49
	v_cmp_gt_f32_e64 s[4:5], v1, v49
	v_cmp_ge_f32_e64 s[6:7], v3, v49
	v_addc_co_u32_e64 v73, s[8:9], 0, v73, s[0:1]
	v_addc_co_u32_e64 v73, s[8:9], 0, v73, s[2:3]
	v_addc_co_u32_e64 v73, s[8:9], 0, v73, s[4:5]
	v_addc_co_u32_e64 v73, s[8:9], 0, v73, s[6:7]
	v_cmp_ge_f32_e64 s[0:1], v5, v49
	v_cmp_ge_f32_e64 s[2:3], v7, v49
	v_cmp_ge_f32_e64 s[4:5], v9, v49
	v_cmp_ge_f32_e64 s[6:7], v11, v49
	v_addc_co_u32_e64 v73, s[8:9], 0, v73, s[0:1]
	v_addc_co_u32_e64 v73, s[8:9], 0, v73, s[2:3]
	v_addc_co_u32_e64 v73, s[8:9], 0, v73, s[4:5]
	v_addc_co_u32_e64 v73, s[8:9], 0, v73, s[6:7]
	v_cmp_ge_f32_e64 s[0:1], v13, v49
	v_cmp_ge_f32_e64 s[2:3], v15, v49
	v_cmp_gt_f32_e64 s[4:5], v19, v49
	v_cmp_gt_f32_e64 s[6:7], v21, v49
	v_addc_co_u32_e64 v73, s[8:9], 0, v73, s[0:1]
	v_addc_co_u32_e64 v73, s[8:9], 0, v73, s[2:3]
	v_addc_co_u32_e64 v73, s[8:9], 0, v73, s[4:5]
	v_addc_co_u32_e64 v73, s[8:9], 0, v73, s[6:7]
	v_cmp_gt_f32_e64 s[0:1], v23, v49
	v_cmp_gt_f32_e64 s[2:3], v25, v49
	v_cmp_gt_f32_e64 s[4:5], v27, v49
	v_cmp_gt_f32_e64 s[6:7], v29, v49
	v_addc_co_u32_e64 v73, s[8:9], 0, v73, s[0:1]
	v_addc_co_u32_e64 v73, s[8:9], 0, v73, s[2:3]
	v_addc_co_u32_e64 v73, s[8:9], 0, v73, s[4:5]
	v_addc_co_u32_e64 v73, s[8:9], 0, v73, s[6:7]
	v_cmp_gt_f32_e64 s[0:1], v31, v49
	v_cmp_gt_f32_e64 s[2:3], v33, v49
	s_nop 1
	v_addc_co_u32_e64 v73, s[8:9], 0, v73, s[0:1]
	v_addc_co_u32_e64 v73, s[8:9], 0, v73, s[2:3]
	s_and_b64 s[14:15], s[14:15], s[10:11]
	s_or_b64 s[12:13], s[12:13], s[14:15]
	v_or_b32_e32 v74, 14, v154
	v_addc_co_u32_e64 v73, s[8:9], 0, v73, s[12:13]
	v_cmp_le_u32_e64 s[0:1], v74, v0
	v_lshlrev_b32_e64 v75, v74, 1
	v_cmp_gt_u32_e64 s[2:3], 16, v73
	s_and_b64 s[0:1], s[0:1], s[2:3]
	v_cndmask_b32_e64 v75, 0, v75, s[0:1]
	v_or_b32_e32 v70, v70, v75
	v_mov_b32_e32 v73, 0
	v_cmp_gt_f32_e64 s[12:13], v19, v51
	v_cmp_eq_f32_e64 s[14:15], v19, v51
	v_cmp_ge_f32_e64 s[0:1], v35, v51
	v_cmp_ge_f32_e64 s[2:3], v37, v51
	v_cmp_ge_f32_e64 s[4:5], v39, v51
	v_cmp_ge_f32_e64 s[6:7], v41, v51
	v_addc_co_u32_e64 v73, s[8:9], 0, v73, s[0:1]
	v_addc_co_u32_e64 v73, s[8:9], 0, v73, s[2:3]
	v_addc_co_u32_e64 v73, s[8:9], 0, v73, s[4:5]
	v_addc_co_u32_e64 v73, s[8:9], 0, v73, s[6:7]
	v_cmp_ge_f32_e64 s[0:1], v43, v51
	v_cmp_ge_f32_e64 s[2:3], v45, v51
	v_cmp_ge_f32_e64 s[4:5], v47, v51
	v_cmp_ge_f32_e64 s[6:7], v49, v51
	v_addc_co_u32_e64 v73, s[8:9], 0, v73, s[0:1]
	v_addc_co_u32_e64 v73, s[8:9], 0, v73, s[2:3]
	v_addc_co_u32_e64 v73, s[8:9], 0, v73, s[4:5]
	v_addc_co_u32_e64 v73, s[8:9], 0, v73, s[6:7]
	v_cmp_gt_f32_e64 s[0:1], v53, v51
	v_cmp_gt_f32_e64 s[2:3], v55, v51
	v_cmp_gt_f32_e64 s[4:5], v57, v51
	v_cmp_gt_f32_e64 s[6:7], v59, v51
	v_addc_co_u32_e64 v73, s[8:9], 0, v73, s[0:1]
	v_addc_co_u32_e64 v73, s[8:9], 0, v73, s[2:3]
	v_addc_co_u32_e64 v73, s[8:9], 0, v73, s[4:5]
	v_addc_co_u32_e64 v73, s[8:9], 0, v73, s[6:7]
	v_cmp_gt_f32_e64 s[0:1], v61, v51
	v_cmp_gt_f32_e64 s[2:3], v63, v51
	v_cmp_gt_f32_e64 s[4:5], v1, v51
	v_cmp_ge_f32_e64 s[6:7], v3, v51
	v_addc_co_u32_e64 v73, s[8:9], 0, v73, s[0:1]
	v_addc_co_u32_e64 v73, s[8:9], 0, v73, s[2:3]
	v_addc_co_u32_e64 v73, s[8:9], 0, v73, s[4:5]
	v_addc_co_u32_e64 v73, s[8:9], 0, v73, s[6:7]
	v_cmp_ge_f32_e64 s[0:1], v5, v51
	v_cmp_ge_f32_e64 s[2:3], v7, v51
	v_cmp_ge_f32_e64 s[4:5], v9, v51
	v_cmp_ge_f32_e64 s[6:7], v11, v51
	v_addc_co_u32_e64 v73, s[8:9], 0, v73, s[0:1]
	v_addc_co_u32_e64 v73, s[8:9], 0, v73, s[2:3]
	v_addc_co_u32_e64 v73, s[8:9], 0, v73, s[4:5]
	v_addc_co_u32_e64 v73, s[8:9], 0, v73, s[6:7]
	v_cmp_ge_f32_e64 s[0:1], v13, v51
	v_cmp_ge_f32_e64 s[2:3], v15, v51
	v_cmp_ge_f32_e64 s[4:5], v17, v51
	v_cmp_gt_f32_e64 s[6:7], v21, v51
	v_addc_co_u32_e64 v73, s[8:9], 0, v73, s[0:1]
	v_addc_co_u32_e64 v73, s[8:9], 0, v73, s[2:3]
	v_addc_co_u32_e64 v73, s[8:9], 0, v73, s[4:5]
	v_addc_co_u32_e64 v73, s[8:9], 0, v73, s[6:7]
	v_cmp_gt_f32_e64 s[0:1], v23, v51
	v_cmp_gt_f32_e64 s[2:3], v25, v51
	v_cmp_gt_f32_e64 s[4:5], v27, v51
	v_cmp_gt_f32_e64 s[6:7], v29, v51
	v_addc_co_u32_e64 v73, s[8:9], 0, v73, s[0:1]
	v_addc_co_u32_e64 v73, s[8:9], 0, v73, s[2:3]
	v_addc_co_u32_e64 v73, s[8:9], 0, v73, s[4:5]
	v_addc_co_u32_e64 v73, s[8:9], 0, v73, s[6:7]
	v_cmp_gt_f32_e64 s[0:1], v31, v51
	v_cmp_gt_f32_e64 s[2:3], v33, v51
	s_nop 1
	v_addc_co_u32_e64 v73, s[8:9], 0, v73, s[0:1]
	v_addc_co_u32_e64 v73, s[8:9], 0, v73, s[2:3]
	s_and_b64 s[14:15], s[14:15], s[10:11]
	s_or_b64 s[12:13], s[12:13], s[14:15]
	v_or_b32_e32 v74, 16, v154
	v_addc_co_u32_e64 v73, s[8:9], 0, v73, s[12:13]
	v_cmp_le_u32_e64 s[0:1], v74, v0
	v_lshlrev_b32_e64 v75, v74, 1
	v_cmp_gt_u32_e64 s[2:3], 16, v73
	s_and_b64 s[0:1], s[0:1], s[2:3]
	v_cndmask_b32_e64 v75, 0, v75, s[0:1]
	v_or_b32_e32 v70, v70, v75
	v_mov_b32_e32 v73, 0
	v_cmp_gt_f32_e64 s[12:13], v21, v53
	v_cmp_eq_f32_e64 s[14:15], v21, v53
	v_cmp_ge_f32_e64 s[0:1], v35, v53
	v_cmp_ge_f32_e64 s[2:3], v37, v53
	v_cmp_ge_f32_e64 s[4:5], v39, v53
	v_cmp_ge_f32_e64 s[6:7], v41, v53
	v_addc_co_u32_e64 v73, s[8:9], 0, v73, s[0:1]
	v_addc_co_u32_e64 v73, s[8:9], 0, v73, s[2:3]
	v_addc_co_u32_e64 v73, s[8:9], 0, v73, s[4:5]
	v_addc_co_u32_e64 v73, s[8:9], 0, v73, s[6:7]
	v_cmp_ge_f32_e64 s[0:1], v43, v53
	v_cmp_ge_f32_e64 s[2:3], v45, v53
	v_cmp_ge_f32_e64 s[4:5], v47, v53
	v_cmp_ge_f32_e64 s[6:7], v49, v53
	v_addc_co_u32_e64 v73, s[8:9], 0, v73, s[0:1]
	v_addc_co_u32_e64 v73, s[8:9], 0, v73, s[2:3]
	v_addc_co_u32_e64 v73, s[8:9], 0, v73, s[4:5]
	v_addc_co_u32_e64 v73, s[8:9], 0, v73, s[6:7]
	v_cmp_ge_f32_e64 s[0:1], v51, v53
	v_cmp_gt_f32_e64 s[2:3], v55, v53
	v_cmp_gt_f32_e64 s[4:5], v57, v53
	v_cmp_gt_f32_e64 s[6:7], v59, v53
	v_addc_co_u32_e64 v73, s[8:9], 0, v73, s[0:1]
	v_addc_co_u32_e64 v73, s[8:9], 0, v73, s[2:3]
	v_addc_co_u32_e64 v73, s[8:9], 0, v73, s[4:5]
	v_addc_co_u32_e64 v73, s[8:9], 0, v73, s[6:7]
	v_cmp_gt_f32_e64 s[0:1], v61, v53
	v_cmp_gt_f32_e64 s[2:3], v63, v53
	v_cmp_gt_f32_e64 s[4:5], v1, v53
	v_cmp_ge_f32_e64 s[6:7], v3, v53
	v_addc_co_u32_e64 v73, s[8:9], 0, v73, s[0:1]
	v_addc_co_u32_e64 v73, s[8:9], 0, v73, s[2:3]
	v_addc_co_u32_e64 v73, s[8:9], 0, v73, s[4:5]
	v_addc_co_u32_e64 v73, s[8:9], 0, v73, s[6:7]
	v_cmp_ge_f32_e64 s[0:1], v5, v53
	v_cmp_ge_f32_e64 s[2:3], v7, v53
	v_cmp_ge_f32_e64 s[4:5], v9, v53
	v_cmp_ge_f32_e64 s[6:7], v11, v53
	v_addc_co_u32_e64 v73, s[8:9], 0, v73, s[0:1]
	v_addc_co_u32_e64 v73, s[8:9], 0, v73, s[2:3]
	v_addc_co_u32_e64 v73, s[8:9], 0, v73, s[4:5]
	v_addc_co_u32_e64 v73, s[8:9], 0, v73, s[6:7]
	v_cmp_ge_f32_e64 s[0:1], v13, v53
	v_cmp_ge_f32_e64 s[2:3], v15, v53
	v_cmp_ge_f32_e64 s[4:5], v17, v53
	v_cmp_ge_f32_e64 s[6:7], v19, v53
	v_addc_co_u32_e64 v73, s[8:9], 0, v73, s[0:1]
	v_addc_co_u32_e64 v73, s[8:9], 0, v73, s[2:3]
	v_addc_co_u32_e64 v73, s[8:9], 0, v73, s[4:5]
	v_addc_co_u32_e64 v73, s[8:9], 0, v73, s[6:7]
	v_cmp_gt_f32_e64 s[0:1], v23, v53
	v_cmp_gt_f32_e64 s[2:3], v25, v53
	v_cmp_gt_f32_e64 s[4:5], v27, v53
	v_cmp_gt_f32_e64 s[6:7], v29, v53
	v_addc_co_u32_e64 v73, s[8:9], 0, v73, s[0:1]
	v_addc_co_u32_e64 v73, s[8:9], 0, v73, s[2:3]
	v_addc_co_u32_e64 v73, s[8:9], 0, v73, s[4:5]
	v_addc_co_u32_e64 v73, s[8:9], 0, v73, s[6:7]
	v_cmp_gt_f32_e64 s[0:1], v31, v53
	v_cmp_gt_f32_e64 s[2:3], v33, v53
	s_nop 1
	v_addc_co_u32_e64 v73, s[8:9], 0, v73, s[0:1]
	v_addc_co_u32_e64 v73, s[8:9], 0, v73, s[2:3]
	s_and_b64 s[14:15], s[14:15], s[10:11]
	s_or_b64 s[12:13], s[12:13], s[14:15]
	v_or_b32_e32 v74, 18, v154
	v_addc_co_u32_e64 v73, s[8:9], 0, v73, s[12:13]
	v_cmp_le_u32_e64 s[0:1], v74, v0
	v_lshlrev_b32_e64 v75, v74, 1
	v_cmp_gt_u32_e64 s[2:3], 16, v73
	s_and_b64 s[0:1], s[0:1], s[2:3]
	v_cndmask_b32_e64 v75, 0, v75, s[0:1]
	v_or_b32_e32 v70, v70, v75
	v_mov_b32_e32 v73, 0
	v_cmp_gt_f32_e64 s[12:13], v23, v55
	v_cmp_eq_f32_e64 s[14:15], v23, v55
	v_cmp_ge_f32_e64 s[0:1], v35, v55
	v_cmp_ge_f32_e64 s[2:3], v37, v55
	v_cmp_ge_f32_e64 s[4:5], v39, v55
	v_cmp_ge_f32_e64 s[6:7], v41, v55
	v_addc_co_u32_e64 v73, s[8:9], 0, v73, s[0:1]
	v_addc_co_u32_e64 v73, s[8:9], 0, v73, s[2:3]
	v_addc_co_u32_e64 v73, s[8:9], 0, v73, s[4:5]
	v_addc_co_u32_e64 v73, s[8:9], 0, v73, s[6:7]
	v_cmp_ge_f32_e64 s[0:1], v43, v55
	v_cmp_ge_f32_e64 s[2:3], v45, v55
	v_cmp_ge_f32_e64 s[4:5], v47, v55
	v_cmp_ge_f32_e64 s[6:7], v49, v55
	v_addc_co_u32_e64 v73, s[8:9], 0, v73, s[0:1]
	v_addc_co_u32_e64 v73, s[8:9], 0, v73, s[2:3]
	v_addc_co_u32_e64 v73, s[8:9], 0, v73, s[4:5]
	v_addc_co_u32_e64 v73, s[8:9], 0, v73, s[6:7]
	v_cmp_ge_f32_e64 s[0:1], v51, v55
	v_cmp_ge_f32_e64 s[2:3], v53, v55
	v_cmp_gt_f32_e64 s[4:5], v57, v55
	v_cmp_gt_f32_e64 s[6:7], v59, v55
	v_addc_co_u32_e64 v73, s[8:9], 0, v73, s[0:1]
	v_addc_co_u32_e64 v73, s[8:9], 0, v73, s[2:3]
	v_addc_co_u32_e64 v73, s[8:9], 0, v73, s[4:5]
	v_addc_co_u32_e64 v73, s[8:9], 0, v73, s[6:7]
	v_cmp_gt_f32_e64 s[0:1], v61, v55
	v_cmp_gt_f32_e64 s[2:3], v63, v55
	v_cmp_gt_f32_e64 s[4:5], v1, v55
	v_cmp_ge_f32_e64 s[6:7], v3, v55
	v_addc_co_u32_e64 v73, s[8:9], 0, v73, s[0:1]
	v_addc_co_u32_e64 v73, s[8:9], 0, v73, s[2:3]
	v_addc_co_u32_e64 v73, s[8:9], 0, v73, s[4:5]
	v_addc_co_u32_e64 v73, s[8:9], 0, v73, s[6:7]
	v_cmp_ge_f32_e64 s[0:1], v5, v55
	v_cmp_ge_f32_e64 s[2:3], v7, v55
	v_cmp_ge_f32_e64 s[4:5], v9, v55
	v_cmp_ge_f32_e64 s[6:7], v11, v55
	v_addc_co_u32_e64 v73, s[8:9], 0, v73, s[0:1]
	v_addc_co_u32_e64 v73, s[8:9], 0, v73, s[2:3]
	v_addc_co_u32_e64 v73, s[8:9], 0, v73, s[4:5]
	v_addc_co_u32_e64 v73, s[8:9], 0, v73, s[6:7]
	v_cmp_ge_f32_e64 s[0:1], v13, v55
	v_cmp_ge_f32_e64 s[2:3], v15, v55
	v_cmp_ge_f32_e64 s[4:5], v17, v55
	v_cmp_ge_f32_e64 s[6:7], v19, v55
	v_addc_co_u32_e64 v73, s[8:9], 0, v73, s[0:1]
	v_addc_co_u32_e64 v73, s[8:9], 0, v73, s[2:3]
	v_addc_co_u32_e64 v73, s[8:9], 0, v73, s[4:5]
	v_addc_co_u32_e64 v73, s[8:9], 0, v73, s[6:7]
	v_cmp_ge_f32_e64 s[0:1], v21, v55
	v_cmp_gt_f32_e64 s[2:3], v25, v55
	v_cmp_gt_f32_e64 s[4:5], v27, v55
	v_cmp_gt_f32_e64 s[6:7], v29, v55
	v_addc_co_u32_e64 v73, s[8:9], 0, v73, s[0:1]
	v_addc_co_u32_e64 v73, s[8:9], 0, v73, s[2:3]
	v_addc_co_u32_e64 v73, s[8:9], 0, v73, s[4:5]
	v_addc_co_u32_e64 v73, s[8:9], 0, v73, s[6:7]
	v_cmp_gt_f32_e64 s[0:1], v31, v55
	v_cmp_gt_f32_e64 s[2:3], v33, v55
	s_nop 1
	v_addc_co_u32_e64 v73, s[8:9], 0, v73, s[0:1]
	v_addc_co_u32_e64 v73, s[8:9], 0, v73, s[2:3]
	s_and_b64 s[14:15], s[14:15], s[10:11]
	s_or_b64 s[12:13], s[12:13], s[14:15]
	v_or_b32_e32 v74, 20, v154
	v_addc_co_u32_e64 v73, s[8:9], 0, v73, s[12:13]
	v_cmp_le_u32_e64 s[0:1], v74, v0
	v_lshlrev_b32_e64 v75, v74, 1
	v_cmp_gt_u32_e64 s[2:3], 16, v73
	s_and_b64 s[0:1], s[0:1], s[2:3]
	v_cndmask_b32_e64 v75, 0, v75, s[0:1]
	v_or_b32_e32 v70, v70, v75
	v_mov_b32_e32 v73, 0
	v_cmp_gt_f32_e64 s[12:13], v25, v57
	v_cmp_eq_f32_e64 s[14:15], v25, v57
	v_cmp_ge_f32_e64 s[0:1], v35, v57
	v_cmp_ge_f32_e64 s[2:3], v37, v57
	v_cmp_ge_f32_e64 s[4:5], v39, v57
	v_cmp_ge_f32_e64 s[6:7], v41, v57
	v_addc_co_u32_e64 v73, s[8:9], 0, v73, s[0:1]
	v_addc_co_u32_e64 v73, s[8:9], 0, v73, s[2:3]
	v_addc_co_u32_e64 v73, s[8:9], 0, v73, s[4:5]
	v_addc_co_u32_e64 v73, s[8:9], 0, v73, s[6:7]
	v_cmp_ge_f32_e64 s[0:1], v43, v57
	v_cmp_ge_f32_e64 s[2:3], v45, v57
	v_cmp_ge_f32_e64 s[4:5], v47, v57
	v_cmp_ge_f32_e64 s[6:7], v49, v57
	v_addc_co_u32_e64 v73, s[8:9], 0, v73, s[0:1]
	v_addc_co_u32_e64 v73, s[8:9], 0, v73, s[2:3]
	v_addc_co_u32_e64 v73, s[8:9], 0, v73, s[4:5]
	v_addc_co_u32_e64 v73, s[8:9], 0, v73, s[6:7]
	v_cmp_ge_f32_e64 s[0:1], v51, v57
	v_cmp_ge_f32_e64 s[2:3], v53, v57
	v_cmp_ge_f32_e64 s[4:5], v55, v57
	v_cmp_gt_f32_e64 s[6:7], v59, v57
	v_addc_co_u32_e64 v73, s[8:9], 0, v73, s[0:1]
	v_addc_co_u32_e64 v73, s[8:9], 0, v73, s[2:3]
	v_addc_co_u32_e64 v73, s[8:9], 0, v73, s[4:5]
	v_addc_co_u32_e64 v73, s[8:9], 0, v73, s[6:7]
	v_cmp_gt_f32_e64 s[0:1], v61, v57
	v_cmp_gt_f32_e64 s[2:3], v63, v57
	v_cmp_gt_f32_e64 s[4:5], v1, v57
	v_cmp_ge_f32_e64 s[6:7], v3, v57
	v_addc_co_u32_e64 v73, s[8:9], 0, v73, s[0:1]
	v_addc_co_u32_e64 v73, s[8:9], 0, v73, s[2:3]
	v_addc_co_u32_e64 v73, s[8:9], 0, v73, s[4:5]
	v_addc_co_u32_e64 v73, s[8:9], 0, v73, s[6:7]
	v_cmp_ge_f32_e64 s[0:1], v5, v57
	v_cmp_ge_f32_e64 s[2:3], v7, v57
	v_cmp_ge_f32_e64 s[4:5], v9, v57
	v_cmp_ge_f32_e64 s[6:7], v11, v57
	v_addc_co_u32_e64 v73, s[8:9], 0, v73, s[0:1]
	v_addc_co_u32_e64 v73, s[8:9], 0, v73, s[2:3]
	v_addc_co_u32_e64 v73, s[8:9], 0, v73, s[4:5]
	v_addc_co_u32_e64 v73, s[8:9], 0, v73, s[6:7]
	v_cmp_ge_f32_e64 s[0:1], v13, v57
	v_cmp_ge_f32_e64 s[2:3], v15, v57
	v_cmp_ge_f32_e64 s[4:5], v17, v57
	v_cmp_ge_f32_e64 s[6:7], v19, v57
	v_addc_co_u32_e64 v73, s[8:9], 0, v73, s[0:1]
	v_addc_co_u32_e64 v73, s[8:9], 0, v73, s[2:3]
	v_addc_co_u32_e64 v73, s[8:9], 0, v73, s[4:5]
	v_addc_co_u32_e64 v73, s[8:9], 0, v73, s[6:7]
	v_cmp_ge_f32_e64 s[0:1], v21, v57
	v_cmp_ge_f32_e64 s[2:3], v23, v57
	v_cmp_gt_f32_e64 s[4:5], v27, v57
	v_cmp_gt_f32_e64 s[6:7], v29, v57
	v_addc_co_u32_e64 v73, s[8:9], 0, v73, s[0:1]
	v_addc_co_u32_e64 v73, s[8:9], 0, v73, s[2:3]
	v_addc_co_u32_e64 v73, s[8:9], 0, v73, s[4:5]
	v_addc_co_u32_e64 v73, s[8:9], 0, v73, s[6:7]
	v_cmp_gt_f32_e64 s[0:1], v31, v57
	v_cmp_gt_f32_e64 s[2:3], v33, v57
	s_nop 1
	v_addc_co_u32_e64 v73, s[8:9], 0, v73, s[0:1]
	v_addc_co_u32_e64 v73, s[8:9], 0, v73, s[2:3]
	s_and_b64 s[14:15], s[14:15], s[10:11]
	s_or_b64 s[12:13], s[12:13], s[14:15]
	v_or_b32_e32 v74, 22, v154
	v_addc_co_u32_e64 v73, s[8:9], 0, v73, s[12:13]
	v_cmp_le_u32_e64 s[0:1], v74, v0
	v_lshlrev_b32_e64 v75, v74, 1
	v_cmp_gt_u32_e64 s[2:3], 16, v73
	s_and_b64 s[0:1], s[0:1], s[2:3]
	v_cndmask_b32_e64 v75, 0, v75, s[0:1]
	v_or_b32_e32 v70, v70, v75
	v_mov_b32_e32 v73, 0
	v_cmp_gt_f32_e64 s[12:13], v27, v59
	v_cmp_eq_f32_e64 s[14:15], v27, v59
	v_cmp_ge_f32_e64 s[0:1], v35, v59
	v_cmp_ge_f32_e64 s[2:3], v37, v59
	v_cmp_ge_f32_e64 s[4:5], v39, v59
	v_cmp_ge_f32_e64 s[6:7], v41, v59
	v_addc_co_u32_e64 v73, s[8:9], 0, v73, s[0:1]
	v_addc_co_u32_e64 v73, s[8:9], 0, v73, s[2:3]
	v_addc_co_u32_e64 v73, s[8:9], 0, v73, s[4:5]
	v_addc_co_u32_e64 v73, s[8:9], 0, v73, s[6:7]
	v_cmp_ge_f32_e64 s[0:1], v43, v59
	v_cmp_ge_f32_e64 s[2:3], v45, v59
	v_cmp_ge_f32_e64 s[4:5], v47, v59
	v_cmp_ge_f32_e64 s[6:7], v49, v59
	v_addc_co_u32_e64 v73, s[8:9], 0, v73, s[0:1]
	v_addc_co_u32_e64 v73, s[8:9], 0, v73, s[2:3]
	v_addc_co_u32_e64 v73, s[8:9], 0, v73, s[4:5]
	v_addc_co_u32_e64 v73, s[8:9], 0, v73, s[6:7]
	v_cmp_ge_f32_e64 s[0:1], v51, v59
	v_cmp_ge_f32_e64 s[2:3], v53, v59
	v_cmp_ge_f32_e64 s[4:5], v55, v59
	v_cmp_ge_f32_e64 s[6:7], v57, v59
	v_addc_co_u32_e64 v73, s[8:9], 0, v73, s[0:1]
	v_addc_co_u32_e64 v73, s[8:9], 0, v73, s[2:3]
	v_addc_co_u32_e64 v73, s[8:9], 0, v73, s[4:5]
	v_addc_co_u32_e64 v73, s[8:9], 0, v73, s[6:7]
	v_cmp_gt_f32_e64 s[0:1], v61, v59
	v_cmp_gt_f32_e64 s[2:3], v63, v59
	v_cmp_gt_f32_e64 s[4:5], v1, v59
	v_cmp_ge_f32_e64 s[6:7], v3, v59
	v_addc_co_u32_e64 v73, s[8:9], 0, v73, s[0:1]
	v_addc_co_u32_e64 v73, s[8:9], 0, v73, s[2:3]
	v_addc_co_u32_e64 v73, s[8:9], 0, v73, s[4:5]
	v_addc_co_u32_e64 v73, s[8:9], 0, v73, s[6:7]
	v_cmp_ge_f32_e64 s[0:1], v5, v59
	v_cmp_ge_f32_e64 s[2:3], v7, v59
	v_cmp_ge_f32_e64 s[4:5], v9, v59
	v_cmp_ge_f32_e64 s[6:7], v11, v59
	v_addc_co_u32_e64 v73, s[8:9], 0, v73, s[0:1]
	v_addc_co_u32_e64 v73, s[8:9], 0, v73, s[2:3]
	v_addc_co_u32_e64 v73, s[8:9], 0, v73, s[4:5]
	v_addc_co_u32_e64 v73, s[8:9], 0, v73, s[6:7]
	v_cmp_ge_f32_e64 s[0:1], v13, v59
	v_cmp_ge_f32_e64 s[2:3], v15, v59
	v_cmp_ge_f32_e64 s[4:5], v17, v59
	v_cmp_ge_f32_e64 s[6:7], v19, v59
	v_addc_co_u32_e64 v73, s[8:9], 0, v73, s[0:1]
	v_addc_co_u32_e64 v73, s[8:9], 0, v73, s[2:3]
	v_addc_co_u32_e64 v73, s[8:9], 0, v73, s[4:5]
	v_addc_co_u32_e64 v73, s[8:9], 0, v73, s[6:7]
	v_cmp_ge_f32_e64 s[0:1], v21, v59
	v_cmp_ge_f32_e64 s[2:3], v23, v59
	v_cmp_ge_f32_e64 s[4:5], v25, v59
	v_cmp_gt_f32_e64 s[6:7], v29, v59
	v_addc_co_u32_e64 v73, s[8:9], 0, v73, s[0:1]
	v_addc_co_u32_e64 v73, s[8:9], 0, v73, s[2:3]
	v_addc_co_u32_e64 v73, s[8:9], 0, v73, s[4:5]
	v_addc_co_u32_e64 v73, s[8:9], 0, v73, s[6:7]
	v_cmp_gt_f32_e64 s[0:1], v31, v59
	v_cmp_gt_f32_e64 s[2:3], v33, v59
	s_nop 1
	v_addc_co_u32_e64 v73, s[8:9], 0, v73, s[0:1]
	v_addc_co_u32_e64 v73, s[8:9], 0, v73, s[2:3]
	s_and_b64 s[14:15], s[14:15], s[10:11]
	s_or_b64 s[12:13], s[12:13], s[14:15]
	v_or_b32_e32 v74, 24, v154
	v_addc_co_u32_e64 v73, s[8:9], 0, v73, s[12:13]
	v_cmp_le_u32_e64 s[0:1], v74, v0
	v_lshlrev_b32_e64 v75, v74, 1
	v_cmp_gt_u32_e64 s[2:3], 16, v73
	s_and_b64 s[0:1], s[0:1], s[2:3]
	v_cndmask_b32_e64 v75, 0, v75, s[0:1]
	v_or_b32_e32 v70, v70, v75
	v_mov_b32_e32 v73, 0
	v_cmp_gt_f32_e64 s[12:13], v29, v61
	v_cmp_eq_f32_e64 s[14:15], v29, v61
	v_cmp_ge_f32_e64 s[0:1], v35, v61
	v_cmp_ge_f32_e64 s[2:3], v37, v61
	v_cmp_ge_f32_e64 s[4:5], v39, v61
	v_cmp_ge_f32_e64 s[6:7], v41, v61
	v_addc_co_u32_e64 v73, s[8:9], 0, v73, s[0:1]
	v_addc_co_u32_e64 v73, s[8:9], 0, v73, s[2:3]
	v_addc_co_u32_e64 v73, s[8:9], 0, v73, s[4:5]
	v_addc_co_u32_e64 v73, s[8:9], 0, v73, s[6:7]
	v_cmp_ge_f32_e64 s[0:1], v43, v61
	v_cmp_ge_f32_e64 s[2:3], v45, v61
	v_cmp_ge_f32_e64 s[4:5], v47, v61
	v_cmp_ge_f32_e64 s[6:7], v49, v61
	v_addc_co_u32_e64 v73, s[8:9], 0, v73, s[0:1]
	v_addc_co_u32_e64 v73, s[8:9], 0, v73, s[2:3]
	v_addc_co_u32_e64 v73, s[8:9], 0, v73, s[4:5]
	v_addc_co_u32_e64 v73, s[8:9], 0, v73, s[6:7]
	v_cmp_ge_f32_e64 s[0:1], v51, v61
	v_cmp_ge_f32_e64 s[2:3], v53, v61
	v_cmp_ge_f32_e64 s[4:5], v55, v61
	v_cmp_ge_f32_e64 s[6:7], v57, v61
	v_addc_co_u32_e64 v73, s[8:9], 0, v73, s[0:1]
	v_addc_co_u32_e64 v73, s[8:9], 0, v73, s[2:3]
	v_addc_co_u32_e64 v73, s[8:9], 0, v73, s[4:5]
	v_addc_co_u32_e64 v73, s[8:9], 0, v73, s[6:7]
	v_cmp_ge_f32_e64 s[0:1], v59, v61
	v_cmp_gt_f32_e64 s[2:3], v63, v61
	v_cmp_gt_f32_e64 s[4:5], v1, v61
	v_cmp_ge_f32_e64 s[6:7], v3, v61
	v_addc_co_u32_e64 v73, s[8:9], 0, v73, s[0:1]
	v_addc_co_u32_e64 v73, s[8:9], 0, v73, s[2:3]
	v_addc_co_u32_e64 v73, s[8:9], 0, v73, s[4:5]
	v_addc_co_u32_e64 v73, s[8:9], 0, v73, s[6:7]
	v_cmp_ge_f32_e64 s[0:1], v5, v61
	v_cmp_ge_f32_e64 s[2:3], v7, v61
	v_cmp_ge_f32_e64 s[4:5], v9, v61
	v_cmp_ge_f32_e64 s[6:7], v11, v61
	v_addc_co_u32_e64 v73, s[8:9], 0, v73, s[0:1]
	v_addc_co_u32_e64 v73, s[8:9], 0, v73, s[2:3]
	v_addc_co_u32_e64 v73, s[8:9], 0, v73, s[4:5]
	v_addc_co_u32_e64 v73, s[8:9], 0, v73, s[6:7]
	v_cmp_ge_f32_e64 s[0:1], v13, v61
	v_cmp_ge_f32_e64 s[2:3], v15, v61
	v_cmp_ge_f32_e64 s[4:5], v17, v61
	v_cmp_ge_f32_e64 s[6:7], v19, v61
	v_addc_co_u32_e64 v73, s[8:9], 0, v73, s[0:1]
	v_addc_co_u32_e64 v73, s[8:9], 0, v73, s[2:3]
	v_addc_co_u32_e64 v73, s[8:9], 0, v73, s[4:5]
	v_addc_co_u32_e64 v73, s[8:9], 0, v73, s[6:7]
	v_cmp_ge_f32_e64 s[0:1], v21, v61
	v_cmp_ge_f32_e64 s[2:3], v23, v61
	v_cmp_ge_f32_e64 s[4:5], v25, v61
	v_cmp_ge_f32_e64 s[6:7], v27, v61
	v_addc_co_u32_e64 v73, s[8:9], 0, v73, s[0:1]
	v_addc_co_u32_e64 v73, s[8:9], 0, v73, s[2:3]
	v_addc_co_u32_e64 v73, s[8:9], 0, v73, s[4:5]
	v_addc_co_u32_e64 v73, s[8:9], 0, v73, s[6:7]
	v_cmp_gt_f32_e64 s[0:1], v31, v61
	v_cmp_gt_f32_e64 s[2:3], v33, v61
	s_nop 1
	v_addc_co_u32_e64 v73, s[8:9], 0, v73, s[0:1]
	v_addc_co_u32_e64 v73, s[8:9], 0, v73, s[2:3]
	s_and_b64 s[14:15], s[14:15], s[10:11]
	s_or_b64 s[12:13], s[12:13], s[14:15]
	v_or_b32_e32 v74, 26, v154
	v_addc_co_u32_e64 v73, s[8:9], 0, v73, s[12:13]
	v_cmp_le_u32_e64 s[0:1], v74, v0
	v_lshlrev_b32_e64 v75, v74, 1
	v_cmp_gt_u32_e64 s[2:3], 16, v73
	s_and_b64 s[0:1], s[0:1], s[2:3]
	v_cndmask_b32_e64 v75, 0, v75, s[0:1]
	v_or_b32_e32 v70, v70, v75
	v_mov_b32_e32 v73, 0
	v_cmp_gt_f32_e64 s[12:13], v31, v63
	v_cmp_eq_f32_e64 s[14:15], v31, v63
	v_cmp_ge_f32_e64 s[0:1], v35, v63
	v_cmp_ge_f32_e64 s[2:3], v37, v63
	v_cmp_ge_f32_e64 s[4:5], v39, v63
	v_cmp_ge_f32_e64 s[6:7], v41, v63
	v_addc_co_u32_e64 v73, s[8:9], 0, v73, s[0:1]
	v_addc_co_u32_e64 v73, s[8:9], 0, v73, s[2:3]
	v_addc_co_u32_e64 v73, s[8:9], 0, v73, s[4:5]
	v_addc_co_u32_e64 v73, s[8:9], 0, v73, s[6:7]
	v_cmp_ge_f32_e64 s[0:1], v43, v63
	v_cmp_ge_f32_e64 s[2:3], v45, v63
	v_cmp_ge_f32_e64 s[4:5], v47, v63
	v_cmp_ge_f32_e64 s[6:7], v49, v63
	v_addc_co_u32_e64 v73, s[8:9], 0, v73, s[0:1]
	v_addc_co_u32_e64 v73, s[8:9], 0, v73, s[2:3]
	v_addc_co_u32_e64 v73, s[8:9], 0, v73, s[4:5]
	v_addc_co_u32_e64 v73, s[8:9], 0, v73, s[6:7]
	v_cmp_ge_f32_e64 s[0:1], v51, v63
	v_cmp_ge_f32_e64 s[2:3], v53, v63
	v_cmp_ge_f32_e64 s[4:5], v55, v63
	v_cmp_ge_f32_e64 s[6:7], v57, v63
	v_addc_co_u32_e64 v73, s[8:9], 0, v73, s[0:1]
	v_addc_co_u32_e64 v73, s[8:9], 0, v73, s[2:3]
	v_addc_co_u32_e64 v73, s[8:9], 0, v73, s[4:5]
	v_addc_co_u32_e64 v73, s[8:9], 0, v73, s[6:7]
	v_cmp_ge_f32_e64 s[0:1], v59, v63
	v_cmp_ge_f32_e64 s[2:3], v61, v63
	v_cmp_gt_f32_e64 s[4:5], v1, v63
	v_cmp_ge_f32_e64 s[6:7], v3, v63
	v_addc_co_u32_e64 v73, s[8:9], 0, v73, s[0:1]
	v_addc_co_u32_e64 v73, s[8:9], 0, v73, s[2:3]
	v_addc_co_u32_e64 v73, s[8:9], 0, v73, s[4:5]
	v_addc_co_u32_e64 v73, s[8:9], 0, v73, s[6:7]
	v_cmp_ge_f32_e64 s[0:1], v5, v63
	v_cmp_ge_f32_e64 s[2:3], v7, v63
	v_cmp_ge_f32_e64 s[4:5], v9, v63
	v_cmp_ge_f32_e64 s[6:7], v11, v63
	v_addc_co_u32_e64 v73, s[8:9], 0, v73, s[0:1]
	v_addc_co_u32_e64 v73, s[8:9], 0, v73, s[2:3]
	v_addc_co_u32_e64 v73, s[8:9], 0, v73, s[4:5]
	v_addc_co_u32_e64 v73, s[8:9], 0, v73, s[6:7]
	v_cmp_ge_f32_e64 s[0:1], v13, v63
	v_cmp_ge_f32_e64 s[2:3], v15, v63
	v_cmp_ge_f32_e64 s[4:5], v17, v63
	v_cmp_ge_f32_e64 s[6:7], v19, v63
	v_addc_co_u32_e64 v73, s[8:9], 0, v73, s[0:1]
	v_addc_co_u32_e64 v73, s[8:9], 0, v73, s[2:3]
	v_addc_co_u32_e64 v73, s[8:9], 0, v73, s[4:5]
	v_addc_co_u32_e64 v73, s[8:9], 0, v73, s[6:7]
	v_cmp_ge_f32_e64 s[0:1], v21, v63
	v_cmp_ge_f32_e64 s[2:3], v23, v63
	v_cmp_ge_f32_e64 s[4:5], v25, v63
	v_cmp_ge_f32_e64 s[6:7], v27, v63
	v_addc_co_u32_e64 v73, s[8:9], 0, v73, s[0:1]
	v_addc_co_u32_e64 v73, s[8:9], 0, v73, s[2:3]
	v_addc_co_u32_e64 v73, s[8:9], 0, v73, s[4:5]
	v_addc_co_u32_e64 v73, s[8:9], 0, v73, s[6:7]
	v_cmp_ge_f32_e64 s[0:1], v29, v63
	v_cmp_gt_f32_e64 s[2:3], v33, v63
	s_nop 1
	v_addc_co_u32_e64 v73, s[8:9], 0, v73, s[0:1]
	v_addc_co_u32_e64 v73, s[8:9], 0, v73, s[2:3]
	s_and_b64 s[14:15], s[14:15], s[10:11]
	s_or_b64 s[12:13], s[12:13], s[14:15]
	v_or_b32_e32 v74, 28, v154
	v_addc_co_u32_e64 v73, s[8:9], 0, v73, s[12:13]
	v_cmp_le_u32_e64 s[0:1], v74, v0
	v_lshlrev_b32_e64 v75, v74, 1
	v_cmp_gt_u32_e64 s[2:3], 16, v73
	s_and_b64 s[0:1], s[0:1], s[2:3]
	v_cndmask_b32_e64 v75, 0, v75, s[0:1]
	v_or_b32_e32 v70, v70, v75
	v_mov_b32_e32 v73, 0
	v_cmp_gt_f32_e64 s[12:13], v33, v1
	v_cmp_eq_f32_e64 s[14:15], v33, v1
	v_cmp_ge_f32_e64 s[0:1], v35, v1
	v_cmp_ge_f32_e64 s[2:3], v37, v1
	v_cmp_ge_f32_e64 s[4:5], v39, v1
	v_cmp_ge_f32_e64 s[6:7], v41, v1
	v_addc_co_u32_e64 v73, s[8:9], 0, v73, s[0:1]
	v_addc_co_u32_e64 v73, s[8:9], 0, v73, s[2:3]
	v_addc_co_u32_e64 v73, s[8:9], 0, v73, s[4:5]
	v_addc_co_u32_e64 v73, s[8:9], 0, v73, s[6:7]
	v_cmp_ge_f32_e64 s[0:1], v43, v1
	v_cmp_ge_f32_e64 s[2:3], v45, v1
	v_cmp_ge_f32_e64 s[4:5], v47, v1
	v_cmp_ge_f32_e64 s[6:7], v49, v1
	v_addc_co_u32_e64 v73, s[8:9], 0, v73, s[0:1]
	v_addc_co_u32_e64 v73, s[8:9], 0, v73, s[2:3]
	v_addc_co_u32_e64 v73, s[8:9], 0, v73, s[4:5]
	v_addc_co_u32_e64 v73, s[8:9], 0, v73, s[6:7]
	v_cmp_ge_f32_e64 s[0:1], v51, v1
	v_cmp_ge_f32_e64 s[2:3], v53, v1
	v_cmp_ge_f32_e64 s[4:5], v55, v1
	v_cmp_ge_f32_e64 s[6:7], v57, v1
	v_addc_co_u32_e64 v73, s[8:9], 0, v73, s[0:1]
	v_addc_co_u32_e64 v73, s[8:9], 0, v73, s[2:3]
	v_addc_co_u32_e64 v73, s[8:9], 0, v73, s[4:5]
	v_addc_co_u32_e64 v73, s[8:9], 0, v73, s[6:7]
	v_cmp_ge_f32_e64 s[0:1], v59, v1
	v_cmp_ge_f32_e64 s[2:3], v61, v1
	v_cmp_ge_f32_e64 s[4:5], v63, v1
	v_cmp_ge_f32_e64 s[6:7], v3, v1
	v_addc_co_u32_e64 v73, s[8:9], 0, v73, s[0:1]
	v_addc_co_u32_e64 v73, s[8:9], 0, v73, s[2:3]
	v_addc_co_u32_e64 v73, s[8:9], 0, v73, s[4:5]
	v_addc_co_u32_e64 v73, s[8:9], 0, v73, s[6:7]
	v_cmp_ge_f32_e64 s[0:1], v5, v1
	v_cmp_ge_f32_e64 s[2:3], v7, v1
	v_cmp_ge_f32_e64 s[4:5], v9, v1
	v_cmp_ge_f32_e64 s[6:7], v11, v1
	v_addc_co_u32_e64 v73, s[8:9], 0, v73, s[0:1]
	v_addc_co_u32_e64 v73, s[8:9], 0, v73, s[2:3]
	v_addc_co_u32_e64 v73, s[8:9], 0, v73, s[4:5]
	v_addc_co_u32_e64 v73, s[8:9], 0, v73, s[6:7]
	v_cmp_ge_f32_e64 s[0:1], v13, v1
	v_cmp_ge_f32_e64 s[2:3], v15, v1
	v_cmp_ge_f32_e64 s[4:5], v17, v1
	v_cmp_ge_f32_e64 s[6:7], v19, v1
	v_addc_co_u32_e64 v73, s[8:9], 0, v73, s[0:1]
	v_addc_co_u32_e64 v73, s[8:9], 0, v73, s[2:3]
	v_addc_co_u32_e64 v73, s[8:9], 0, v73, s[4:5]
	v_addc_co_u32_e64 v73, s[8:9], 0, v73, s[6:7]
	v_cmp_ge_f32_e64 s[0:1], v21, v1
	v_cmp_ge_f32_e64 s[2:3], v23, v1
	v_cmp_ge_f32_e64 s[4:5], v25, v1
	v_cmp_ge_f32_e64 s[6:7], v27, v1
	v_addc_co_u32_e64 v73, s[8:9], 0, v73, s[0:1]
	v_addc_co_u32_e64 v73, s[8:9], 0, v73, s[2:3]
	v_addc_co_u32_e64 v73, s[8:9], 0, v73, s[4:5]
	v_addc_co_u32_e64 v73, s[8:9], 0, v73, s[6:7]
	v_cmp_ge_f32_e64 s[0:1], v29, v1
	v_cmp_ge_f32_e64 s[2:3], v31, v1
	s_nop 1
	v_addc_co_u32_e64 v73, s[8:9], 0, v73, s[0:1]
	v_addc_co_u32_e64 v73, s[8:9], 0, v73, s[2:3]
	s_and_b64 s[14:15], s[14:15], s[10:11]
	s_or_b64 s[12:13], s[12:13], s[14:15]
	v_or_b32_e32 v74, 30, v154
	v_addc_co_u32_e64 v73, s[8:9], 0, v73, s[12:13]
	v_cmp_le_u32_e64 s[0:1], v74, v0
	v_lshlrev_b32_e64 v75, v74, 1
	v_cmp_gt_u32_e64 s[2:3], 16, v73
	s_and_b64 s[0:1], s[0:1], s[2:3]
	v_cndmask_b32_e64 v75, 0, v75, s[0:1]
	v_or_b32_e32 v70, v70, v75
	v_mov_b32_e32 v72, 0
	v_or_b32_e32 v0, v70, v72
	ds_bpermute_b32 v1, v180, v0
	s_and_saveexec_b64 s[0:1], s[38:39]
	v_readlane_b32 s54, v254, 63
	v_readlane_b32 s55, v255, 0
	s_cbranch_execz .LBB0_347
	v_readlane_b32 s2, v255, 23
	s_lshl_b32 s2, s2, 13
	s_add_u32 s2, s54, s2
	s_addc_u32 s3, s55, 0
	v_lshl_add_u64 v[2:3], v[64:65], 2, s[2:3]
	s_waitcnt lgkmcnt(0)
	v_or_b32_e32 v4, v1, v0
	v_add_co_u32_e32 v0, vcc, 0x2d080000, v2
	s_nop 1
	v_addc_co_u32_e32 v1, vcc, 0, v3, vcc
	global_store_dword v[0:1], v4, off
